# scan-loop B-operand DMA hoisted + counted wait; custom wide-store bf16 epilogue (operand-swapped MFMA) in phase 8
# baseline (speedup 1.0000x reference)
; #define MFMA32(a, b, c) __builtin_amdgcn_mfma_f32_32x32x16_bf16((a), (b), (c), 0, 0, 0)
; DI int crow(int reg, int h) { return (reg & 3) + 8 * (reg >> 2) + 4 * h; }
; DI void scan_item(const Params& p, int item, char* smem) {
;     ...
;     {
;       const u32x4* k0 = gQK + n * 512;
;       const u32x4* d0 = gKD + n * 1024;
; #pragma unroll
;       for (int i = 0; i < 2; ++i) GLDS(k0 + tid + i * 256, bufB + tid + i * 256);
; #pragma unroll
;       for (int i = 0; i < 4; ++i) GLDS(d0 + tid + i * 256, bufB + 512 + tid + i * 256);
;     }
;     {
;       bf16x8 Sb[4][2];
; #pragma unroll
;       for (int d = 0; d < 4; ++d) { Sb[d][0] = pack8(S[d], 0); Sb[d][1] = pack8(S[d], 1); }
; #pragma unroll
;       for (int ct = 0; ct < 2; ++ct)
; #pragma unroll
;         for (int q = 0; q < 16; ++q) o[ct][q] = 0.f;
; #pragma unroll
;       for (int ct = 0; ct < 2; ++ct)
; #pragma unroll
;         for (int ks = 0; ks < 8; ++ks) {
;           bf16x8 aw = __builtin_bit_cast(bf16x8, bufA[(ct * 8 + ks) * 64 + lane]);
;           bf16x8 aq = __builtin_bit_cast(bf16x8, bufA[1024 + (ct * 8 + ks) * 64 + lane]);
;           vn[ct] = MFMA32(aw, Sb[ks >> 1][ks & 1], vn[ct]);
;           o[ct] = MFMA32(aq, Sb[ks >> 1][ks & 1], o[ct]);
;         }
;     }
;     bf16x8 Vb[2][2];
; #pragma unroll
;     for (int ct = 0; ct < 2; ++ct) { Vb[ct][0] = pack8(vn[ct], 0); Vb[ct][1] = pack8(vn[ct], 1); }
;     asm volatile("s_waitcnt vmcnt(0)" ::: "memory");
;     __syncthreads();
;     {
;       const u32x4* w1 = gWN + n1 * 1024;
;       const u32x4* q1 = gQD + n1 * 1024;
; #pragma unroll
;       for (int i = 0; i < 4; ++i) {
;         GLDS(w1 + tid + i * 256, bufA + tid + i * 256);
;         GLDS(q1 + tid + i * 256, bufA + 1024 + tid + i * 256);
;       }
;       const float* u1 = gU + n1 * 8192;
; #pragma unroll
;       for (int ct = 0; ct < 2; ++ct)
; #pragma unroll
;         for (int q = 0; q < 16; ++q) vn[ct][q] = u1[(ct * 32 + crow(q, 0)) * 128 + uo];
;     }
; #pragma unroll
;     for (int ct = 0; ct < 2; ++ct)
; #pragma unroll
;       for (int ks = 0; ks < 4; ++ks) {
;         bf16x8 a = __builtin_bit_cast(bf16x8, bufB[(ct * 4 + ks) * 64 + lane]);
;         o[ct] = MFMA32(a, Vb[ks >> 1][ks & 1], o[ct]);
;       }
; #pragma unroll
;     for (int d = 0; d < 4; ++d) {
; #pragma unroll
;       for (int q = 0; q < 16; ++q) S[d][q] *= gl;
.LBB0_700:
	v_readfirstlane_b32 s98, v149
	s_add_u32 s99, s98, 0x8000
	s_mov_b32 m0, s99
	s_add_u32 s96, s2, 0x1000
	s_addc_u32 s97, s3, 0
	global_load_lds_dwordx4 v142, s[2:3]
	s_add_u32 m0, s98, 0x9000
	s_nop 0
	global_load_lds_dwordx4 v142, s[96:97]
	s_add_u32 m0, s98, 0xa000
	s_add_u32 s96, s8, 0x1000
	s_addc_u32 s97, s9, 0
	global_load_lds_dwordx4 v142, s[8:9]
	s_add_u32 m0, s98, 0xb000
	s_nop 0
	global_load_lds_dwordx4 v142, s[96:97]
	s_add_u32 m0, s98, 0xc000
	s_add_u32 s96, s8, 0x2000
	s_addc_u32 s97, s9, 0
	global_load_lds_dwordx4 v142, s[96:97]
	s_add_u32 m0, s98, 0xd000
	s_add_u32 s96, s8, 0x3000
	s_addc_u32 s97, s9, 0
	global_load_lds_dwordx4 v142, s[96:97]
	ds_read_b128 v[96:99], v167
	ds_read_b128 v[104:107], v167 offset:1024
	v_cvt_pk_bf16_f32 v100, v48, v49
	v_cvt_pk_bf16_f32 v101, v50, v51
	v_cvt_pk_bf16_f32 v102, v52, v53
	v_cvt_pk_bf16_f32 v103, v54, v55
	v_cvt_pk_bf16_f32 v128, v56, v57
	v_cvt_pk_bf16_f32 v129, v58, v59
	v_cvt_pk_bf16_f32 v130, v60, v61
	s_waitcnt lgkmcnt(1)
	v_mfma_f32_32x32x16_bf16 v[64:79], v[96:99], v[100:103], v[64:79]
	ds_read_b128 v[96:99], v167 offset:16384
	ds_read_b128 v[108:111], v167 offset:17408
	v_cvt_pk_bf16_f32 v131, v62, v63
	v_cvt_pk_bf16_f32 v132, v32, v33
	v_cvt_pk_bf16_f32 v133, v34, v35
	v_cvt_pk_bf16_f32 v134, v36, v37
	v_cvt_pk_bf16_f32 v135, v38, v39
	v_cvt_pk_bf16_f32 v136, v40, v41
	s_waitcnt lgkmcnt(1)
	v_mfma_f32_32x32x16_bf16 v[112:127], v[96:99], v[100:103], 0
	ds_read_b128 v[96:99], v167 offset:2048
	v_cvt_pk_bf16_f32 v137, v42, v43
	v_cvt_pk_bf16_f32 v138, v44, v45
	v_cvt_pk_bf16_f32 v139, v46, v47
	v_cvt_pk_bf16_f32 v168, v16, v17
	v_cvt_pk_bf16_f32 v169, v18, v19
	v_cvt_pk_bf16_f32 v170, v20, v21
	v_mfma_f32_32x32x16_bf16 v[64:79], v[104:107], v[128:131], v[64:79]
	ds_read_b128 v[104:107], v167 offset:3072
	v_cvt_pk_bf16_f32 v171, v22, v23
	v_cvt_pk_bf16_f32 v172, v24, v25
	v_cvt_pk_bf16_f32 v173, v26, v27
	v_cvt_pk_bf16_f32 v174, v28, v29
	v_cvt_pk_bf16_f32 v175, v30, v31
	v_cvt_pk_bf16_f32 v176, v0, v1
	s_waitcnt lgkmcnt(2)
	v_mfma_f32_32x32x16_bf16 v[112:127], v[108:111], v[128:131], v[112:127]
	v_cvt_pk_bf16_f32 v177, v2, v3
	v_cvt_pk_bf16_f32 v178, v4, v5
	v_cvt_pk_bf16_f32 v179, v6, v7
	v_cvt_pk_bf16_f32 v180, v8, v9
	v_cvt_pk_bf16_f32 v181, v10, v11
	v_cvt_pk_bf16_f32 v182, v12, v13
	v_cvt_pk_bf16_f32 v183, v14, v15
	s_waitcnt lgkmcnt(1)
	v_mfma_f32_32x32x16_bf16 v[64:79], v[96:99], v[132:135], v[64:79]
	ds_read_b128 v[96:99], v167 offset:18432
	ds_read_b128 v[108:111], v167 offset:19456
	s_add_i32 s31, s31, 1
	s_cmpk_lg_i32 s18, 0x780
	s_cselect_b32 s19, s31, 31
	s_waitcnt vmcnt(38)
	v_pk_mul_f32 v[62:63], v[62:63], v[152:153] op_sel_hi:[1,0]
	v_pk_mul_f32 v[60:61], v[60:61], v[152:153] op_sel_hi:[1,0]
	v_pk_mul_f32 v[58:59], v[58:59], v[152:153] op_sel_hi:[1,0]
	s_waitcnt lgkmcnt(1)
	v_mfma_f32_32x32x16_bf16 v[112:127], v[96:99], v[132:135], v[112:127]
	ds_read_b128 v[96:99], v167 offset:4096
	v_mul_f32_e64 v56, v56, v152
	v_mul_f32_e64 v57, v57, v152
	v_mul_f32_e64 v54, v54, v152
	v_mul_f32_e64 v55, v55, v152
	v_pk_mul_f32 v[52:53], v[52:53], v[152:153] op_sel_hi:[1,0]
	v_pk_mul_f32 v[50:51], v[50:51], v[152:153] op_sel_hi:[1,0]
	v_pk_mul_f32 v[48:49], v[48:49], v[152:153] op_sel_hi:[1,0]
	v_pk_mul_f32 v[46:47], v[46:47], v[152:153] op_sel_hi:[1,0]
	v_mfma_f32_32x32x16_bf16 v[64:79], v[104:107], v[136:139], v[64:79]
	ds_read_b128 v[104:107], v167 offset:5120
	v_mul_f32_e64 v44, v44, v152
	v_mul_f32_e64 v45, v45, v152
	v_mul_f32_e64 v42, v42, v152
	v_mul_f32_e64 v43, v43, v152
	v_pk_mul_f32 v[40:41], v[40:41], v[152:153] op_sel_hi:[1,0]
	v_pk_mul_f32 v[38:39], v[38:39], v[152:153] op_sel_hi:[1,0]
	v_pk_mul_f32 v[36:37], v[36:37], v[152:153] op_sel_hi:[1,0]
	v_pk_mul_f32 v[34:35], v[34:35], v[152:153] op_sel_hi:[1,0]
	s_waitcnt lgkmcnt(2)
	v_mfma_f32_32x32x16_bf16 v[112:127], v[108:111], v[136:139], v[112:127]
	v_mul_f32_e64 v32, v32, v152
	v_mul_f32_e64 v33, v33, v152
	v_mul_f32_e64 v30, v30, v152
	v_mul_f32_e64 v31, v31, v152
	v_mul_f32_e64 v28, v28, v152
	v_mul_f32_e64 v29, v29, v152
	v_pk_mul_f32 v[26:27], v[26:27], v[152:153] op_sel_hi:[1,0]
	v_pk_mul_f32 v[24:25], v[24:25], v[152:153] op_sel_hi:[1,0]
	v_pk_mul_f32 v[22:23], v[22:23], v[152:153] op_sel_hi:[1,0]
	v_pk_mul_f32 v[20:21], v[20:21], v[152:153] op_sel_hi:[1,0]
	s_waitcnt lgkmcnt(1)
	v_mfma_f32_32x32x16_bf16 v[64:79], v[96:99], v[168:171], v[64:79]
	ds_read_b128 v[96:99], v167 offset:20480
	ds_read_b128 v[108:111], v167 offset:21504
	v_mul_f32_e64 v18, v18, v152
	v_mul_f32_e64 v19, v19, v152
	v_mul_f32_e64 v16, v16, v152
	v_mul_f32_e64 v17, v17, v152
	v_pk_mul_f32 v[14:15], v[14:15], v[152:153] op_sel_hi:[1,0]
	v_pk_mul_f32 v[12:13], v[12:13], v[152:153] op_sel_hi:[1,0]
	v_pk_mul_f32 v[10:11], v[10:11], v[152:153] op_sel_hi:[1,0]
	v_pk_mul_f32 v[8:9], v[8:9], v[152:153] op_sel_hi:[1,0]
	s_waitcnt lgkmcnt(1)
	v_mfma_f32_32x32x16_bf16 v[112:127], v[96:99], v[168:171], v[112:127]
	ds_read_b128 v[96:99], v167 offset:6144
	v_mul_f32_e64 v6, v6, v152
	v_mul_f32_e64 v7, v7, v152
	v_mul_f32_e64 v4, v4, v152
	v_mul_f32_e64 v5, v5, v152
	v_pk_mul_f32 v[2:3], v[2:3], v[152:153] op_sel_hi:[1,0]
	v_pk_mul_f32 v[0:1], v[0:1], v[152:153] op_sel_hi:[1,0]
	v_mfma_f32_32x32x16_bf16 v[64:79], v[104:107], v[172:175], v[64:79]
	ds_read_b128 v[104:107], v167 offset:7168
	s_waitcnt lgkmcnt(2)
	v_mfma_f32_32x32x16_bf16 v[112:127], v[108:111], v[172:175], v[112:127]
	s_waitcnt lgkmcnt(1)
	v_mfma_f32_32x32x16_bf16 v[64:79], v[96:99], v[176:179], v[64:79]
	ds_read_b128 v[96:99], v167 offset:22528
	ds_read_b128 v[108:111], v167 offset:23552
	s_waitcnt lgkmcnt(1)
; #define MFMA32(a, b, c) __builtin_amdgcn_mfma_f32_32x32x16_bf16((a), (b), (c), 0, 0, 0)
; DI int crow(int reg, int h) { return (reg & 3) + 8 * (reg >> 2) + 4 * h; }
; #define GLDS(gp, lp) __builtin_amdgcn_global_load_lds((const unsigned*)(gp), (unsigned*)(lp), 16, 0, 0)
; DI void scan_item(const Params& p, int item, char* smem) {
;     ...
;       for (int ct = 0; ct < 2; ++ct)
; #pragma unroll
;         for (int ks = 0; ks < 8; ++ks) {
;           bf16x8 aw = __builtin_bit_cast(bf16x8, bufA[(ct * 8 + ks) * 64 + lane]);
;           bf16x8 aq = __builtin_bit_cast(bf16x8, bufA[1024 + (ct * 8 + ks) * 64 + lane]);
;           vn[ct] = MFMA32(aw, Sb[ks >> 1][ks & 1], vn[ct]);
;           o[ct] = MFMA32(aq, Sb[ks >> 1][ks & 1], o[ct]);
;         }
;     }
;     bf16x8 Vb[2][2];
; #pragma unroll
;     for (int ct = 0; ct < 2; ++ct) { Vb[ct][0] = pack8(vn[ct], 0); Vb[ct][1] = pack8(vn[ct], 1); }
;     asm volatile("s_waitcnt vmcnt(0)" ::: "memory");
;     __syncthreads();
;     {
;       const u32x4* w1 = gWN + n1 * 1024;
;       const u32x4* q1 = gQD + n1 * 1024;
; #pragma unroll
;       for (int i = 0; i < 4; ++i) {
;         GLDS(w1 + tid + i * 256, bufA + tid + i * 256);
;         GLDS(q1 + tid + i * 256, bufA + 1024 + tid + i * 256);
;       }
;       const float* u1 = gU + n1 * 8192;
; #pragma unroll
;       for (int ct = 0; ct < 2; ++ct)
; #pragma unroll
;         for (int q = 0; q < 16; ++q) vn[ct][q] = u1[(ct * 32 + crow(q, 0)) * 128 + uo];
;     }
; #pragma unroll
;     for (int ct = 0; ct < 2; ++ct)
; #pragma unroll
;       for (int ks = 0; ks < 4; ++ks) {
;         bf16x8 a = __builtin_bit_cast(bf16x8, bufB[(ct * 4 + ks) * 64 + lane]);
;         o[ct] = MFMA32(a, Vb[ks >> 1][ks & 1], o[ct]);
;       }
	v_mfma_f32_32x32x16_bf16 v[112:127], v[96:99], v[176:179], v[112:127]
	ds_read_b128 v[96:99], v167 offset:8192
	ds_read_b128 v[184:187], v167 offset:9216
	s_waitcnt lgkmcnt(1)
	v_mfma_f32_32x32x16_bf16 v[80:95], v[96:99], v[100:103], v[80:95]
	ds_read_b128 v[96:99], v167 offset:24576
	ds_read_b128 v[188:191], v167 offset:25600
	v_mfma_f32_32x32x16_bf16 v[64:79], v[104:107], v[180:183], v[64:79]
	v_mfma_f32_32x32x16_bf16 v[112:127], v[108:111], v[180:183], v[112:127]
	s_nop 10
	v_cvt_pk_bf16_f32 v64, v64, v65
	v_cvt_pk_bf16_f32 v65, v66, v67
	v_cvt_pk_bf16_f32 v66, v68, v69
	v_cvt_pk_bf16_f32 v67, v70, v71
	s_waitcnt lgkmcnt(1)
	v_mfma_f32_32x32x16_bf16 v[96:111], v[96:99], v[100:103], 0
	v_mfma_f32_32x32x16_bf16 v[80:95], v[184:187], v[128:131], v[80:95]
	s_waitcnt lgkmcnt(0)
	v_mfma_f32_32x32x16_bf16 v[96:111], v[188:191], v[128:131], v[96:111]
	ds_read_b128 v[128:131], v167 offset:10240
	ds_read_b128 v[184:187], v167 offset:11264
	s_waitcnt lgkmcnt(1)
	v_mfma_f32_32x32x16_bf16 v[80:95], v[128:131], v[132:135], v[80:95]
	ds_read_b128 v[128:131], v167 offset:26624
	ds_read_b128 v[188:191], v167 offset:27648
	s_waitcnt lgkmcnt(1)
	v_mfma_f32_32x32x16_bf16 v[96:111], v[128:131], v[132:135], v[96:111]
	v_add_u32_e32 v130, 0x8000, v149
	v_lshl_add_u64 v[128:129], s[2:3], 0, v[142:143]
	v_readfirstlane_b32 s0, v130
	s_mov_b32 m0, s0
	v_lshl_add_u64 v[132:133], v[128:129], 0, s[10:11]
	s_nop 0
	v_add_u32_e32 v128, 0x9000, v149
	v_mfma_f32_32x32x16_bf16 v[80:95], v[184:187], v[136:139], v[80:95]
	v_readfirstlane_b32 s0, v128
	ds_read_b128 v[128:131], v167 offset:12288
	s_mov_b32 m0, s0
	v_add_u32_e32 v186, 0xa000, v149
	s_nop 0
	v_readfirstlane_b32 s0, v186
	s_waitcnt lgkmcnt(0)
	v_mfma_f32_32x32x16_bf16 v[96:111], v[188:191], v[136:139], v[96:111]
	ds_read_b128 v[132:135], v167 offset:28672
	ds_read_b128 v[136:139], v167 offset:13312
	v_add_u32_e32 v188, 0xb000, v149
	v_lshl_add_u64 v[184:185], s[8:9], 0, v[142:143]
	s_mov_b32 m0, s0
	v_readfirstlane_b32 s0, v188
	s_nop 0
	v_mfma_f32_32x32x16_bf16 v[80:95], v[128:131], v[168:171], v[80:95]
	v_lshl_add_u64 v[186:187], v[184:185], 0, s[10:11]
	s_mov_b32 m0, s0
	ds_read_b128 v[128:131], v167 offset:29696
	s_nop 0
	s_waitcnt lgkmcnt(0)
	v_mfma_f32_32x32x16_bf16 v[96:111], v[132:135], v[168:171], v[96:111]
	v_add_u32_e32 v134, 0xc000, v149
	v_lshl_add_u64 v[132:133], v[184:185], 0, s[12:13]
	v_readfirstlane_b32 s0, v134
	s_mov_b32 m0, s0
	s_nop 0
	s_nop 0
	v_add_u32_e32 v132, 0xd000, v149
	v_mfma_f32_32x32x16_bf16 v[80:95], v[136:139], v[172:175], v[80:95]
	v_readfirstlane_b32 s0, v132
	ds_read_b128 v[132:135], v167 offset:14336
	v_lshl_add_u64 v[136:137], v[184:185], 0, s[14:15]
	s_mov_b32 m0, s0
	s_lshl_b32 s0, s19, 10
	s_nop 0
	v_mfma_f32_32x32x16_bf16 v[96:111], v[128:131], v[172:175], v[96:111]
	ds_read_b128 v[128:131], v167 offset:15360
	ds_read_b128 v[136:139], v167 offset:30720
	ds_read_b128 v[168:171], v167 offset:31744
	s_lshl_b64 s[20:21], s[0:1], 4
	v_readfirstlane_b32 s0, v149
	s_mov_b32 m0, s0
	v_readfirstlane_b32 s0, v153
	s_waitcnt vmcnt(0)
	s_waitcnt vmcnt(0) lgkmcnt(0)
	v_mfma_f32_32x32x16_bf16 v[80:95], v[132:135], v[176:179], v[80:95]
	v_lshl_add_u64 v[132:133], v[144:145], 0, s[20:21]
	s_barrier
	v_lshl_add_u64 v[134:135], v[146:147], 0, s[20:21]
	global_load_lds_dwordx4 v[132:133], off
	s_mov_b32 m0, s0
	v_readfirstlane_b32 s0, v154
	v_mfma_f32_32x32x16_bf16 v[96:111], v[136:139], v[176:179], v[96:111]
	global_load_lds_dwordx4 v[134:135], off
	v_lshl_add_u64 v[136:137], v[132:133], 0, s[10:11]
	s_mov_b32 m0, s0
	v_readfirstlane_b32 s0, v155
	global_load_lds_dwordx4 v[136:137], off
	v_mfma_f32_32x32x16_bf16 v[80:95], v[128:131], v[180:183], v[80:95]
	v_lshl_add_u64 v[128:129], v[134:135], 0, s[10:11]
	s_mov_b32 m0, s0
	v_readfirstlane_b32 s0, v156
	global_load_lds_dwordx4 v[128:129], off
	v_lshl_add_u64 v[128:129], v[132:133], 0, s[12:13]
	s_mov_b32 m0, s0
	v_readfirstlane_b32 s0, v158
	global_load_lds_dwordx4 v[128:129], off
	v_lshl_add_u64 v[128:129], v[134:135], 0, s[12:13]
	s_mov_b32 m0, s0
	v_readfirstlane_b32 s0, v160
	global_load_lds_dwordx4 v[128:129], off
	v_lshl_add_u64 v[128:129], v[132:133], 0, s[14:15]
	s_mov_b32 m0, s0
	v_readfirstlane_b32 s0, v162
	global_load_lds_dwordx4 v[128:129], off
	v_lshl_add_u64 v[128:129], v[134:135], 0, s[14:15]
	s_mov_b32 m0, s0
	v_cvt_pk_bf16_f32 v136, v72, v73
	global_load_lds_dwordx4 v[128:129], off
	ds_read_b128 v[128:131], v167 offset:32768
	ds_read_b128 v[68:71], v167 offset:33792
	s_waitcnt lgkmcnt(0)
	v_mfma_f32_32x32x16_bf16 v[112:127], v[128:131], v[64:67], v[112:127]
	v_cvt_pk_bf16_f32 v137, v74, v75
	v_cvt_pk_bf16_f32 v138, v76, v77
	v_cvt_pk_bf16_f32 v139, v78, v79
	v_cvt_pk_bf16_f32 v132, v80, v81
	v_cvt_pk_bf16_f32 v133, v82, v83
	v_cvt_pk_bf16_f32 v134, v84, v85
	v_cvt_pk_bf16_f32 v135, v86, v87
	v_mfma_f32_32x32x16_bf16 v[112:127], v[68:71], v[136:139], v[112:127]
	ds_read_b128 v[68:71], v167 offset:34816
	ds_read_b128 v[72:75], v167 offset:35840
	v_cvt_pk_bf16_f32 v128, v88, v89
	v_cvt_pk_bf16_f32 v129, v90, v91
	v_cvt_pk_bf16_f32 v130, v92, v93
	v_cvt_pk_bf16_f32 v131, v94, v95
	s_lshl_b32 s0, s19, 13
	s_waitcnt lgkmcnt(0)
; #define MFMA32(a, b, c) __builtin_amdgcn_mfma_f32_32x32x16_bf16((a), (b), (c), 0, 0, 0)
; DI int crow(int reg, int h) { return (reg & 3) + 8 * (reg >> 2) + 4 * h; }
; #define GLDS(gp, lp) __builtin_amdgcn_global_load_lds((const unsigned*)(gp), (unsigned*)(lp), 16, 0, 0)
; DI void scan_item(const Params& p, int item, char* smem) {
;     ...
;       const u32x4* w1 = gWN + n1 * 1024;
;       const u32x4* q1 = gQD + n1 * 1024;
; #pragma unroll
;       for (int i = 0; i < 4; ++i) {
;         GLDS(w1 + tid + i * 256, bufA + tid + i * 256);
;         GLDS(q1 + tid + i * 256, bufA + 1024 + tid + i * 256);
;       }
;       const float* u1 = gU + n1 * 8192;
; #pragma unroll
;       for (int ct = 0; ct < 2; ++ct)
; #pragma unroll
;         for (int q = 0; q < 16; ++q) vn[ct][q] = u1[(ct * 32 + crow(q, 0)) * 128 + uo];
;     }
; #pragma unroll
;     for (int ct = 0; ct < 2; ++ct)
; #pragma unroll
;       for (int ks = 0; ks < 4; ++ks) {
;         bf16x8 a = __builtin_bit_cast(bf16x8, bufB[(ct * 4 + ks) * 64 + lane]);
;         o[ct] = MFMA32(a, Vb[ks >> 1][ks & 1], o[ct]);
;       }
; #pragma unroll
;     for (int d = 0; d < 4; ++d) {
; #pragma unroll
;       for (int q = 0; q < 16; ++q) S[d][q] *= gl;
; #pragma unroll
;       for (int ks = 0; ks < 4; ++ks) {
;         bf16x8 a = __builtin_bit_cast(bf16x8, bufB[512 + (d * 4 + ks) * 64 + lane]);
;         S[d] = MFMA32(a, Vb[ks >> 1][ks & 1], S[d]);
;       }
;     }
; #pragma unroll
;     for (int ct = 0; ct < 2; ++ct) op[ct] = o[ct];
;     asm volatile("s_waitcnt vmcnt(0)" ::: "memory");
;     __syncthreads();
	v_mfma_f32_32x32x16_bf16 v[112:127], v[68:71], v[132:135], v[112:127]
	s_lshl_b64 s[20:21], s[0:1], 2
	s_add_u32 s20, s6, s20
	s_addc_u32 s21, s7, s21
	v_lshl_add_u64 v[172:173], s[20:21], 0, v[140:141]
	v_add_co_u32_e32 v80, vcc, s23, v172
	s_add_i32 s18, s18, 64
	v_mfma_f32_32x32x16_bf16 v[96:111], v[168:171], v[180:183], v[96:111]
	v_addc_co_u32_e32 v81, vcc, 0, v173, vcc
	v_add_co_u32_e32 v82, vcc, s25, v172
	s_add_u32 s8, s8, 0x4000
	s_nop 0
	v_addc_co_u32_e32 v83, vcc, 0, v173, vcc
	v_mfma_f32_32x32x16_bf16 v[112:127], v[72:75], v[128:131], v[112:127]
	ds_read_b128 v[68:71], v167 offset:36864
	ds_read_b128 v[72:75], v167 offset:37888
	v_add_co_u32_e32 v88, vcc, s27, v172
	s_addc_u32 s9, s9, 0
	s_nop 0
	v_addc_co_u32_e32 v89, vcc, 0, v173, vcc
	v_add_co_u32_e32 v90, vcc, s22, v172
	s_waitcnt lgkmcnt(0)
	v_mfma_f32_32x32x16_bf16 v[96:111], v[68:71], v[64:67], v[96:111]
	v_addc_co_u32_e32 v91, vcc, 0, v173, vcc
	s_add_u32 s2, s2, 0x2000
	s_addc_u32 s3, s3, 0
	s_add_u32 s16, s16, 4
	s_addc_u32 s17, s17, 0
	s_cmp_lg_u32 s31, 32
	v_mfma_f32_32x32x16_bf16 v[96:111], v[72:75], v[136:139], v[96:111]
	ds_read_b128 v[68:71], v167 offset:38912
	ds_read_b128 v[72:75], v167 offset:39936
	ds_read_b128 v[76:79], v167 offset:46080
	s_waitcnt lgkmcnt(0)
	v_mfma_f32_32x32x16_bf16 v[96:111], v[68:71], v[132:135], v[96:111]
	ds_read_b128 v[68:71], v167 offset:40960
	v_mfma_f32_32x32x16_bf16 v[96:111], v[72:75], v[128:131], v[96:111]
	ds_read_b128 v[72:75], v167 offset:41984
	s_waitcnt lgkmcnt(0)
	v_mfma_f32_32x32x16_bf16 v[48:63], v[68:71], v[64:67], v[48:63]
	ds_read_b128 v[68:71], v167 offset:43008
	v_mfma_f32_32x32x16_bf16 v[48:63], v[72:75], v[136:139], v[48:63]
	ds_read_b128 v[72:75], v167 offset:44032
	s_waitcnt lgkmcnt(0)
	v_mfma_f32_32x32x16_bf16 v[48:63], v[68:71], v[132:135], v[48:63]
	ds_read_b128 v[68:71], v167 offset:45056
	s_waitcnt lgkmcnt(0)
	v_mfma_f32_32x32x16_bf16 v[32:47], v[68:71], v[64:67], v[32:47]
	v_mfma_f32_32x32x16_bf16 v[48:63], v[72:75], v[128:131], v[48:63]
	global_load_dword v68, v166, s[20:21]
	global_load_dword v69, v[80:81], off offset:512
	global_load_dword v70, v[80:81], off offset:1024
	global_load_dword v71, v[80:81], off offset:1536
	global_load_dword v72, v165, s[20:21]
	global_load_dword v73, v[82:83], off offset:512
	global_load_dword v74, v[82:83], off offset:1024
	global_load_dword v75, v[82:83], off offset:1536
	ds_read_b128 v[80:83], v167 offset:47104
	ds_read_b128 v[84:87], v167 offset:48128
	v_mfma_f32_32x32x16_bf16 v[32:47], v[76:79], v[136:139], v[32:47]
	s_waitcnt lgkmcnt(0)
	v_mfma_f32_32x32x16_bf16 v[32:47], v[80:83], v[132:135], v[32:47]
	global_load_dword v76, v164, s[20:21]
	global_load_dword v77, v[88:89], off offset:512
	global_load_dword v78, v[88:89], off offset:1024
	global_load_dword v79, v[88:89], off offset:1536
	global_load_dword v80, v163, s[20:21]
	global_load_dword v81, v[90:91], off offset:512
	global_load_dword v82, v[90:91], off offset:1024
	global_load_dword v83, v[90:91], off offset:1536
	ds_read_b128 v[88:91], v167 offset:49152
	ds_read_b128 v[92:95], v167 offset:51200
	v_mfma_f32_32x32x16_bf16 v[32:47], v[84:87], v[128:131], v[32:47]
	ds_read_b128 v[84:87], v167 offset:50176
	s_waitcnt lgkmcnt(0)
	v_mfma_f32_32x32x16_bf16 v[16:31], v[88:91], v[64:67], v[16:31]
	v_add_co_u32_e32 v88, vcc, s24, v172
	s_nop 1
	v_addc_co_u32_e32 v89, vcc, 0, v173, vcc
	v_add_co_u32_e32 v168, vcc, s26, v172
	v_mfma_f32_32x32x16_bf16 v[16:31], v[84:87], v[136:139], v[16:31]
	s_nop 0
	v_addc_co_u32_e32 v169, vcc, 0, v173, vcc
	global_load_dword v84, v161, s[20:21]
	global_load_dword v85, v[88:89], off offset:512
	global_load_dword v86, v[88:89], off offset:1024
	global_load_dword v87, v[88:89], off offset:1536
	s_nop 0
	global_load_dword v88, v159, s[20:21]
	global_load_dword v89, v[168:169], off offset:512
	global_load_dword v90, v[168:169], off offset:1024
	global_load_dword v91, v[168:169], off offset:1536
	ds_read_b128 v[168:171], v167 offset:52224
	v_add_co_u32_e32 v172, vcc, s28, v172
	v_mfma_f32_32x32x16_bf16 v[16:31], v[92:95], v[132:135], v[16:31]
	ds_read_b128 v[92:95], v167 offset:53248
	v_addc_co_u32_e32 v173, vcc, 0, v173, vcc
	s_waitcnt lgkmcnt(0)
	v_mfma_f32_32x32x16_bf16 v[16:31], v[168:171], v[128:131], v[16:31]
	ds_read_b128 v[168:171], v167 offset:54272
	v_mfma_f32_32x32x16_bf16 v[0:15], v[92:95], v[64:67], v[0:15]
	global_load_dword v64, v140, s[20:21]
	global_load_dword v65, v140, s[20:21] offset:512
	global_load_dword v66, v140, s[20:21] offset:1024
	global_load_dword v67, v140, s[20:21] offset:1536
	global_load_dword v92, v157, s[20:21]
	global_load_dword v93, v[172:173], off offset:512
	global_load_dword v94, v[172:173], off offset:1024
	global_load_dword v95, v[172:173], off offset:1536
	s_waitcnt lgkmcnt(0)
	v_mfma_f32_32x32x16_bf16 v[0:15], v[168:171], v[136:139], v[0:15]
	ds_read_b128 v[136:139], v167 offset:55296
	ds_read_b128 v[168:171], v167 offset:56320
	s_waitcnt vmcnt(0)
	s_waitcnt vmcnt(0) lgkmcnt(0)
	s_barrier
	v_mfma_f32_32x32x16_bf16 v[0:15], v[136:139], v[132:135], v[0:15]
	v_mfma_f32_32x32x16_bf16 v[0:15], v[168:171], v[128:131], v[0:15]
	s_cbranch_scc0 .LBB0_703

; DI void scan_item(const Params& p, int item, char* smem) {
;     ...
;   for (int n = 0; n < 32; ++n) {
;     const int chunk = item * 32 + n;
;     const float gl = p.GL[chunk];
;     const int n1 = (n + 1 < 32) ? n + 1 : 31;
.Lscan_first:
	s_waitcnt vmcnt(0)
	s_branch .LBB0_700

; #define GA_LOAD(pr_) do { _Pragma("unroll") for (int i = 0; i < 4; ++i) ra[i] = *(const u32x4*)(Ab + (i * 32) * lda + (pr_) * 64); } while (0)
; #define GB_LOAD(kt_) do { const bfr* bk_ = Bb + (kt_) * NB * 32; \
;     _Pragma("unroll") for (int i = 0; i < 4; ++i) rb[i] = *(const u32x4*)(bk_ + (i * 64) * 32); } while (0)
; #define G_STORE(kt_) do { bfr* as_ = S0 + ((kt_) & 1) * GSTAGE; bfr* bs_ = as_ + 128 * 40; \
;     if (apar == ((kt_) & 1)) { _Pragma("unroll") for (int i = 0; i < 4; ++i) *(u32x4*)(as_ + asoff + i * 32 * 40) = ra[i]; } \
;     _Pragma("unroll") for (int i = 0; i < 4; ++i) *(u32x4*)(bs_ + bsoff + i * 64 * 40) = rb[i]; } while (0)
; template <int lda>
; DI void gemm_mainloop(const bfr* __restrict__ A, const bfr* __restrict__ Bt, int NB, int K, int m0, int n0, char* smem, f32x16 (&acc)[2][4]) {
;   bfr* S0 = (bfr*)smem;
;   int tid = threadIdx.x;
;   asm volatile("" : "+v"(tid));
;   const int lane = tid & 63, wid = tid >> 6, wr = wid >> 1, wc = wid & 1;
;   const int r = lane & 31, hl = lane >> 5;
; #pragma unroll
;   for (int i = 0; i < 2; ++i)
; #pragma unroll
;     for (int j = 0; j < 4; ++j)
; #pragma unroll
;       for (int q = 0; q < 16; ++q) acc[i][j][q] = 0.f;
;   u32x4 ra[4], rb[4];
;   const int nk = K >> 5;
;   const int arow = tid >> 3, ac8 = tid & 7, apar = ac8 >> 2;
;   const bfr* Ab = A + (m0 + arow) * lda + ac8 * 8;
;   const int asoff = arow * 40 + (ac8 & 3) * 8;
;   const int brow = tid >> 2, bc4 = tid & 3;
;   const bfr* Bb = Bt + (n0 + brow) * 32 + bc4 * 8;
;   const int bsoff = brow * 40 + bc4 * 8;
;     ...
;   GA_LOAD(0);
;   GB_LOAD(0);
;   G_STORE(0);
;   GB_LOAD(1);
;   __syncthreads();
; DI void phase_gemm_bf16out(const Params& p, const bfr* A, const bfr* Wt, bfr* C, int N, const float* ss, char* smem) {
;     ...
;   for (int t0 = blockIdx.x; t0 < 128 * ntn; t0 += gridDim.x) {
;     const int t = ((gridDim.x & 7) == 0) ? xcd_tile(t0, ntn) : t0;
;     int mt = t / ntn, nt = t % ntn;
;     gemm_tile<1024>(A, Wt, N, 1024, mt * 128, nt * 256, smem,
.LBB0_920:
	s_cmpk_gt_i32 s46, 0x1ff
	s_cbranch_scc1 .LBB0_936
	s_and_b32 s0, s34, 7
	s_cmp_eq_u32 s0, 0
	s_cselect_b64 s[0:1], -1, 0
	v_cndmask_b32_e64 v0, 0, 1, s[0:1]
	s_waitcnt lgkmcnt(0)
	s_add_u32 s14, s10, 0x20080
	s_addc_u32 s15, s11, 0
	v_cmp_ne_u32_e64 s[0:1], 1, v0
	v_mov_b32_e32 v199, 0
	s_mov_b32 s17, 0x10000
	s_mov_b32 s19, 0x20000
	s_mov_b32 s22, 0x30000
	s_movk_i32 s23, 0x1000
	s_mov_b32 s24, 0xfffffc0
	s_movk_i32 s25, 0x80
	s_movk_i32 s26, 0x50
	s_mov_b32 s16, 0x3a800000
	s_mov_b32 s18, 0x358637bd
	s_mov_b32 s27, 0x800000
	s_mov_b32 s28, s46
	s_branch .LBB0_923
.LBB0_923:
	s_and_b64 vcc, exec, s[0:1]
	s_mov_b32 s4, s28
	s_cbranch_vccnz .LBB0_925
	s_ashr_i32 s4, s28, 3
	s_lshr_b32 s6, s4, 30
	s_lshl_b32 s5, s28, 4
	s_add_i32 s6, s4, s6
	s_and_b32 s5, s5, 0x70
	s_lshr_b32 s7, s6, 2
	s_add_i32 s7, s7, s5
	s_and_b32 s6, s6, -4
	s_lshl_b32 s5, s7, 2
	s_sub_i32 s4, s4, s6
	s_add_i32 s4, s5, s4
.LBB0_925:
	s_ashr_i32 s5, s4, 31
	s_lshr_b32 s5, s5, 30
	s_add_i32 s5, s4, s5
	s_and_b32 s6, s5, 0xfffffc
	s_lshl_b32 s5, s5, 5
	s_and_b32 s30, s5, 0xffffff80
	s_sub_i32 s4, s4, s6
	s_lshl_b32 s29, s4, 8
	s_mov_b32 s31, 0
	s_mov_b64 s[6:7], 0
	s_lshl_b32 s98, s30, 11
	s_add_u32 s98, s10, s98
	s_addc_u32 s99, s11, 0
	s_lshl_b32 s100, s29, 6
	s_add_u32 s100, s12, s100
	s_addc_u32 s101, s13, 0
	v_writelane_b32 v187, s64, 0
	v_writelane_b32 v187, s65, 1
	v_writelane_b32 v187, s66, 2
	v_writelane_b32 v187, s67, 3
	v_writelane_b32 v187, s68, 4
	v_writelane_b32 v187, s69, 5
	v_writelane_b32 v187, s70, 6
	v_writelane_b32 v187, s71, 7
	v_writelane_b32 v187, s72, 8
	v_writelane_b32 v187, s73, 9
	v_writelane_b32 v187, s74, 10
	v_writelane_b32 v187, s75, 11
	v_writelane_b32 v187, s76, 12
	v_writelane_b32 v187, s77, 13
	v_writelane_b32 v187, s78, 14
	v_writelane_b32 v187, s79, 15
	s_mov_b32 s77, s30
	s_mov_b32 s78, s29
	v_lshrrev_b32_e32 v188, 6, v196
	v_and_b32_e32 v189, 63, v196
	v_readfirstlane_b32 s73, v188
	v_lshrrev_b32_e32 v190, 2, v189
	v_bfe_u32 v191, v189, 4, 2
	v_and_b32_e32 v188, 3, v189
	v_xor_b32_e32 v188, v188, v191
	v_lshlrev_b32_e32 v188, 4, v188
	v_lshl_add_u32 v176, v190, 11, v188
	v_add_u32_e32 v177, 0x8000, v176
	v_lshl_add_u32 v178, v190, 6, v188
	v_and_b32_e32 v190, 31, v189
	v_lshrrev_b32_e32 v191, 5, v189
	v_bfe_u32 v188, v189, 2, 2
	v_xor_b32_e32 v188, v188, v191
	v_lshlrev_b32_e32 v188, 4, v188
	v_lshl_add_u32 v179, v190, 6, v188
	s_lshr_b32 s74, s73, 1
	s_lshl_b32 s74, s74, 12
	s_and_b32 s75, s73, 1
	s_lshl_b32 s75, s75, 13
	v_add_u32_e32 v181, s75, v179
	v_add_u32_e32 v179, s74, v179
	v_xor_b32_e32 v182, 32, v181
	v_xor_b32_e32 v180, 32, v179
	s_lshl_b32 s74, s73, 16
	s_add_u32 s64, s98, s74
	s_addc_u32 s65, s99, 0
	s_lshl_b32 s74, s73, 12
	s_add_u32 s66, s100, s74
	s_addc_u32 s67, s101, 0
	s_lshl_b32 s68, s73, 11
	s_lshl_b32 s69, s73, 12
	s_mov_b32 s70, 0
	s_mov_b32 s71, 0
	s_mov_b32 s72, 0
	s_waitcnt lgkmcnt(0)
	s_barrier
	s_mul_i32 s74, s70, 0x6000
	s_add_u32 s75, s74, s68
	s_mov_b32 m0, s75
	s_add_u32 s76, s74, 0x2000
	s_cmp_eq_u32 s70, 2
	s_cselect_b32 s76, 0x10000, s76
	global_load_lds_dwordx4 v176, s[64:65]
	s_add_u32 m0, s75, 0x400
	s_add_u32 s76, s76, s69
	global_load_lds_dwordx4 v177, s[64:65]
	s_mov_b32 m0, s76
	s_add_u32 s64, s64, 64
	s_addc_u32 s65, s65, 0
	global_load_lds_dwordx4 v178, s[66:67]
	global_load_lds_dwordx4 v178, s[66:67] offset:1024
	global_load_lds_dwordx4 v178, s[66:67] offset:2048
	global_load_lds_dwordx4 v178, s[66:67] offset:3072
	s_add_u32 s66, s66, 0x10000
	s_addc_u32 s67, s67, 0
	s_add_u32 s70, s70, 1
	s_cmp_eq_u32 s70, 3
	s_cselect_b32 s70, 0, s70
	s_mul_i32 s74, s70, 0x6000
	s_add_u32 s75, s74, s68
	s_mov_b32 m0, s75
	s_add_u32 s76, s74, 0x2000
	s_cmp_eq_u32 s70, 2
	s_cselect_b32 s76, 0x10000, s76
	global_load_lds_dwordx4 v176, s[64:65]
	s_add_u32 m0, s75, 0x400
	s_add_u32 s76, s76, s69
	global_load_lds_dwordx4 v177, s[64:65]
	s_mov_b32 m0, s76
	s_add_u32 s64, s64, 64
	s_addc_u32 s65, s65, 0
	global_load_lds_dwordx4 v178, s[66:67]
	global_load_lds_dwordx4 v178, s[66:67] offset:1024
	global_load_lds_dwordx4 v178, s[66:67] offset:2048
	global_load_lds_dwordx4 v178, s[66:67] offset:3072
	s_add_u32 s66, s66, 0x10000
	s_addc_u32 s67, s67, 0
	s_add_u32 s70, s70, 1
	s_cmp_eq_u32 s70, 3
	s_cselect_b32 s70, 0, s70
	v_mov_b32_e32 v112, 0
	v_mov_b32_e32 v113, 0
	v_mov_b32_e32 v114, 0
	v_mov_b32_e32 v115, 0
	v_mov_b32_e32 v116, 0
	v_mov_b32_e32 v117, 0
	v_mov_b32_e32 v118, 0
	v_mov_b32_e32 v119, 0
	v_mov_b32_e32 v120, 0
	v_mov_b32_e32 v121, 0
	v_mov_b32_e32 v122, 0
	v_mov_b32_e32 v123, 0
	v_mov_b32_e32 v124, 0
	v_mov_b32_e32 v125, 0
	v_mov_b32_e32 v126, 0
	v_mov_b32_e32 v127, 0
	v_mov_b32_e32 v96, 0
	v_mov_b32_e32 v97, 0
	v_mov_b32_e32 v98, 0
	v_mov_b32_e32 v99, 0
	v_mov_b32_e32 v100, 0
	v_mov_b32_e32 v101, 0
	v_mov_b32_e32 v102, 0
	v_mov_b32_e32 v103, 0
	v_mov_b32_e32 v104, 0
	v_mov_b32_e32 v105, 0
	v_mov_b32_e32 v106, 0
	v_mov_b32_e32 v107, 0
	v_mov_b32_e32 v108, 0
	v_mov_b32_e32 v109, 0
	v_mov_b32_e32 v110, 0
	v_mov_b32_e32 v111, 0
	v_mov_b32_e32 v80, 0
	v_mov_b32_e32 v81, 0
	v_mov_b32_e32 v82, 0
	v_mov_b32_e32 v83, 0
	v_mov_b32_e32 v84, 0
	v_mov_b32_e32 v85, 0
	v_mov_b32_e32 v86, 0
	v_mov_b32_e32 v87, 0
	v_mov_b32_e32 v88, 0
	v_mov_b32_e32 v89, 0
	v_mov_b32_e32 v90, 0
	v_mov_b32_e32 v91, 0
	v_mov_b32_e32 v92, 0
	v_mov_b32_e32 v93, 0
	v_mov_b32_e32 v94, 0
	v_mov_b32_e32 v95, 0
	v_mov_b32_e32 v64, 0
	v_mov_b32_e32 v65, 0
	v_mov_b32_e32 v66, 0
	v_mov_b32_e32 v67, 0
	v_mov_b32_e32 v68, 0
	v_mov_b32_e32 v69, 0
	v_mov_b32_e32 v70, 0
	v_mov_b32_e32 v71, 0
	v_mov_b32_e32 v72, 0
	v_mov_b32_e32 v73, 0
	v_mov_b32_e32 v74, 0
	v_mov_b32_e32 v75, 0
	v_mov_b32_e32 v76, 0
	v_mov_b32_e32 v77, 0
; #define MFMA32(a, b, c) __builtin_amdgcn_mfma_f32_32x32x16_bf16((a), (b), (c), 0, 0, 0)
; #define GA_LOAD(pr_) do { _Pragma("unroll") for (int i = 0; i < 4; ++i) ra[i] = *(const u32x4*)(Ab + (i * 32) * lda + (pr_) * 64); } while (0)
; #define GB_LOAD(kt_) do { const bfr* bk_ = Bb + (kt_) * NB * 32; \
;     _Pragma("unroll") for (int i = 0; i < 4; ++i) rb[i] = *(const u32x4*)(bk_ + (i * 64) * 32); } while (0)
; #define G_STORE(kt_) do { bfr* as_ = S0 + ((kt_) & 1) * GSTAGE; bfr* bs_ = as_ + 128 * 40; \
;     if (apar == ((kt_) & 1)) { _Pragma("unroll") for (int i = 0; i < 4; ++i) *(u32x4*)(as_ + asoff + i * 32 * 40) = ra[i]; } \
;     _Pragma("unroll") for (int i = 0; i < 4; ++i) *(u32x4*)(bs_ + bsoff + i * 64 * 40) = rb[i]; } while (0)
; template <int lda>
; DI void gemm_mainloop(const bfr* __restrict__ A, const bfr* __restrict__ Bt, int NB, int K, int m0, int n0, char* smem, f32x16 (&acc)[2][4]) {
;     ...
; #pragma unroll
;   for (int i = 0; i < 2; ++i)
; #pragma unroll
;     for (int j = 0; j < 4; ++j)
; #pragma unroll
;       for (int q = 0; q < 16; ++q) acc[i][j][q] = 0.f;
;   u32x4 ra[4], rb[4];
;   const int nk = K >> 5;
;   const int arow = tid >> 3, ac8 = tid & 7, apar = ac8 >> 2;
;   const bfr* Ab = A + (m0 + arow) * lda + ac8 * 8;
;   const int asoff = arow * 40 + (ac8 & 3) * 8;
;   const int brow = tid >> 2, bc4 = tid & 3;
;   const bfr* Bb = Bt + (n0 + brow) * 32 + bc4 * 8;
;   const int bsoff = brow * 40 + bc4 * 8;
;     ...
;   GA_LOAD(0);
;   GB_LOAD(0);
;   G_STORE(0);
;   GB_LOAD(1);
;   __syncthreads();
;   for (int kt = 0; kt < nk; ++kt) {
;     if (kt + 1 < nk) G_STORE(kt + 1);
;     if (kt + 2 < nk) {
;       GB_LOAD(kt + 2);
;       if ((kt & 1) == 0) GA_LOAD((kt >> 1) + 1);
;     }
;     const bfr* As = S0 + (kt & 1) * GSTAGE;
;     const bfr* Bs = As + 128 * 40;
; #pragma unroll
;     for (int ks = 0; ks < 2; ++ks) {
;       bf16x8 af[2], bfg[4];
; #pragma unroll
;       for (int i = 0; i < 2; ++i) af[i] = *(const bf16x8*)(As + (wr * 64 + i * 32 + r) * 40 + ks * 16 + hl * 8);
; #pragma unroll
;       for (int j = 0; j < 4; ++j) bfg[j] = *(const bf16x8*)(Bs + (wc * 128 + j * 32 + r) * 40 + ks * 16 + hl * 8);
; #pragma unroll
;       for (int i = 0; i < 2; ++i)
; #pragma unroll
;         for (int j = 0; j < 4; ++j) acc[i][j] = MFMA32(af[i], bfg[j], acc[i][j]);
;     }
;     __syncthreads();
	v_mov_b32_e32 v78, 0
	v_mov_b32_e32 v79, 0
	v_mov_b32_e32 v48, 0
	v_mov_b32_e32 v49, 0
	v_mov_b32_e32 v50, 0
	v_mov_b32_e32 v51, 0
	v_mov_b32_e32 v52, 0
	v_mov_b32_e32 v53, 0
	v_mov_b32_e32 v54, 0
	v_mov_b32_e32 v55, 0
	v_mov_b32_e32 v56, 0
	v_mov_b32_e32 v57, 0
	v_mov_b32_e32 v58, 0
	v_mov_b32_e32 v59, 0
	v_mov_b32_e32 v60, 0
	v_mov_b32_e32 v61, 0
	v_mov_b32_e32 v62, 0
	v_mov_b32_e32 v63, 0
	v_mov_b32_e32 v32, 0
	v_mov_b32_e32 v33, 0
	v_mov_b32_e32 v34, 0
	v_mov_b32_e32 v35, 0
	v_mov_b32_e32 v36, 0
	v_mov_b32_e32 v37, 0
	v_mov_b32_e32 v38, 0
	v_mov_b32_e32 v39, 0
	v_mov_b32_e32 v40, 0
	v_mov_b32_e32 v41, 0
	v_mov_b32_e32 v42, 0
	v_mov_b32_e32 v43, 0
	v_mov_b32_e32 v44, 0
	v_mov_b32_e32 v45, 0
	v_mov_b32_e32 v46, 0
	v_mov_b32_e32 v47, 0
	v_mov_b32_e32 v16, 0
	v_mov_b32_e32 v17, 0
	v_mov_b32_e32 v18, 0
	v_mov_b32_e32 v19, 0
	v_mov_b32_e32 v20, 0
	v_mov_b32_e32 v21, 0
	v_mov_b32_e32 v22, 0
	v_mov_b32_e32 v23, 0
	v_mov_b32_e32 v24, 0
	v_mov_b32_e32 v25, 0
	v_mov_b32_e32 v26, 0
	v_mov_b32_e32 v27, 0
	v_mov_b32_e32 v28, 0
	v_mov_b32_e32 v29, 0
	v_mov_b32_e32 v30, 0
	v_mov_b32_e32 v31, 0
	v_mov_b32_e32 v0, 0
	v_mov_b32_e32 v1, 0
	v_mov_b32_e32 v2, 0
	v_mov_b32_e32 v3, 0
	v_mov_b32_e32 v4, 0
	v_mov_b32_e32 v5, 0
	v_mov_b32_e32 v6, 0
	v_mov_b32_e32 v7, 0
	v_mov_b32_e32 v8, 0
	v_mov_b32_e32 v9, 0
	v_mov_b32_e32 v10, 0
	v_mov_b32_e32 v11, 0
	v_mov_b32_e32 v12, 0
	v_mov_b32_e32 v13, 0
	v_mov_b32_e32 v14, 0
	v_mov_b32_e32 v15, 0
.Lp8_loop:
	s_waitcnt vmcnt(6)
	s_barrier
	s_mul_i32 s74, s71, 0x6000
	s_add_u32 s75, s74, 0x2000
	s_cmp_eq_u32 s71, 2
	s_cselect_b32 s75, 0x10000, s75
	v_add_u32_e32 v183, s74, v179
	v_add_u32_e32 v185, s75, v181
	v_add_u32_e32 v184, s74, v180
	v_add_u32_e32 v186, s75, v182
	ds_read_b128 v[128:131], v183
	ds_read_b128 v[144:147], v185
	ds_read_b128 v[148:151], v185 offset:2048
	ds_read_b128 v[152:155], v185 offset:4096
	ds_read_b128 v[156:159], v185 offset:6144
	ds_read_b128 v[132:135], v183 offset:2048
	ds_read_b128 v[136:139], v184
	ds_read_b128 v[160:163], v186
	ds_read_b128 v[164:167], v186 offset:2048
	ds_read_b128 v[168:171], v186 offset:4096
	ds_read_b128 v[172:175], v186 offset:6144
	ds_read_b128 v[140:143], v184 offset:2048
	s_add_u32 s71, s71, 1
	s_cmp_eq_u32 s71, 3
	s_cselect_b32 s71, 0, s71
	s_waitcnt lgkmcnt(10)
	v_mfma_f32_32x32x16_bf16 v[112:127], v[144:147], v[128:131], v[112:127]
	s_mul_i32 s74, s70, 0x6000
	s_add_u32 s75, s74, s68
	s_mov_b32 m0, s75
	s_add_u32 s76, s74, 0x2000
	s_cmp_eq_u32 s70, 2
	s_cselect_b32 s76, 0x10000, s76
	global_load_lds_dwordx4 v176, s[64:65]
	s_waitcnt lgkmcnt(9)
	v_mfma_f32_32x32x16_bf16 v[96:111], v[148:151], v[128:131], v[96:111]
	s_add_u32 m0, s75, 0x400
	s_add_u32 s76, s76, s69
	global_load_lds_dwordx4 v177, s[64:65]
	s_waitcnt lgkmcnt(8)
	v_mfma_f32_32x32x16_bf16 v[80:95], v[152:155], v[128:131], v[80:95]
	s_mov_b32 m0, s76
	s_add_u32 s64, s64, 64
	s_addc_u32 s65, s65, 0
	global_load_lds_dwordx4 v178, s[66:67]
	s_waitcnt lgkmcnt(7)
	v_mfma_f32_32x32x16_bf16 v[64:79], v[156:159], v[128:131], v[64:79]
	global_load_lds_dwordx4 v178, s[66:67] offset:1024
	s_waitcnt lgkmcnt(6)
	v_mfma_f32_32x32x16_bf16 v[48:63], v[144:147], v[132:135], v[48:63]
	global_load_lds_dwordx4 v178, s[66:67] offset:2048
	v_mfma_f32_32x32x16_bf16 v[32:47], v[148:151], v[132:135], v[32:47]
	global_load_lds_dwordx4 v178, s[66:67] offset:3072
	s_add_u32 s66, s66, 0x10000
	s_addc_u32 s67, s67, 0
	v_mfma_f32_32x32x16_bf16 v[16:31], v[152:155], v[132:135], v[16:31]
	s_add_u32 s70, s70, 1
	s_cmp_eq_u32 s70, 3
	s_cselect_b32 s70, 0, s70
	v_mfma_f32_32x32x16_bf16 v[0:15], v[156:159], v[132:135], v[0:15]
	s_waitcnt lgkmcnt(4)
	v_mfma_f32_32x32x16_bf16 v[112:127], v[160:163], v[136:139], v[112:127]
	s_waitcnt lgkmcnt(3)
	v_mfma_f32_32x32x16_bf16 v[96:111], v[164:167], v[136:139], v[96:111]
	s_waitcnt lgkmcnt(2)
	v_mfma_f32_32x32x16_bf16 v[80:95], v[168:171], v[136:139], v[80:95]
	s_waitcnt lgkmcnt(1)
	v_mfma_f32_32x32x16_bf16 v[64:79], v[172:175], v[136:139], v[64:79]
	s_waitcnt lgkmcnt(0)
	v_mfma_f32_32x32x16_bf16 v[48:63], v[160:163], v[140:143], v[48:63]
	v_mfma_f32_32x32x16_bf16 v[32:47], v[164:167], v[140:143], v[32:47]
	v_mfma_f32_32x32x16_bf16 v[16:31], v[168:171], v[140:143], v[16:31]
	v_mfma_f32_32x32x16_bf16 v[0:15], v[172:175], v[140:143], v[0:15]
	s_add_u32 s72, s72, 1
	s_cmp_lt_u32 s72, 30
	s_cbranch_scc1 .Lp8_loop
	s_waitcnt vmcnt(6)
	s_barrier
	s_mul_i32 s74, s71, 0x6000
	s_add_u32 s75, s74, 0x2000
	s_cmp_eq_u32 s71, 2
	s_cselect_b32 s75, 0x10000, s75
	v_add_u32_e32 v183, s74, v179
	v_add_u32_e32 v185, s75, v181
	v_add_u32_e32 v184, s74, v180
	v_add_u32_e32 v186, s75, v182
	ds_read_b128 v[128:131], v183
	ds_read_b128 v[144:147], v185
	ds_read_b128 v[148:151], v185 offset:2048
	ds_read_b128 v[152:155], v185 offset:4096
	ds_read_b128 v[156:159], v185 offset:6144
	ds_read_b128 v[132:135], v183 offset:2048
	ds_read_b128 v[136:139], v184
	ds_read_b128 v[160:163], v186
	ds_read_b128 v[164:167], v186 offset:2048
	ds_read_b128 v[168:171], v186 offset:4096
	ds_read_b128 v[172:175], v186 offset:6144
	ds_read_b128 v[140:143], v184 offset:2048
	s_add_u32 s71, s71, 1
	s_cmp_eq_u32 s71, 3
	s_cselect_b32 s71, 0, s71
	s_waitcnt lgkmcnt(10)
	v_mfma_f32_32x32x16_bf16 v[112:127], v[144:147], v[128:131], v[112:127]
	s_waitcnt lgkmcnt(9)
	v_mfma_f32_32x32x16_bf16 v[96:111], v[148:151], v[128:131], v[96:111]
	s_waitcnt lgkmcnt(8)
	v_mfma_f32_32x32x16_bf16 v[80:95], v[152:155], v[128:131], v[80:95]
	s_waitcnt lgkmcnt(7)
	v_mfma_f32_32x32x16_bf16 v[64:79], v[156:159], v[128:131], v[64:79]
	s_waitcnt lgkmcnt(6)
	v_mfma_f32_32x32x16_bf16 v[48:63], v[144:147], v[132:135], v[48:63]
	v_mfma_f32_32x32x16_bf16 v[32:47], v[148:151], v[132:135], v[32:47]
	v_mfma_f32_32x32x16_bf16 v[16:31], v[152:155], v[132:135], v[16:31]
	v_mfma_f32_32x32x16_bf16 v[0:15], v[156:159], v[132:135], v[0:15]
	s_waitcnt lgkmcnt(4)
	v_mfma_f32_32x32x16_bf16 v[112:127], v[160:163], v[136:139], v[112:127]
	s_waitcnt lgkmcnt(3)
	v_mfma_f32_32x32x16_bf16 v[96:111], v[164:167], v[136:139], v[96:111]
	s_waitcnt lgkmcnt(2)
	v_mfma_f32_32x32x16_bf16 v[80:95], v[168:171], v[136:139], v[80:95]
	s_waitcnt lgkmcnt(1)
	v_mfma_f32_32x32x16_bf16 v[64:79], v[172:175], v[136:139], v[64:79]
	s_waitcnt lgkmcnt(0)
	v_mfma_f32_32x32x16_bf16 v[48:63], v[160:163], v[140:143], v[48:63]
	v_mfma_f32_32x32x16_bf16 v[32:47], v[164:167], v[140:143], v[32:47]
	v_mfma_f32_32x32x16_bf16 v[16:31], v[168:171], v[140:143], v[16:31]
	v_mfma_f32_32x32x16_bf16 v[0:15], v[172:175], v[140:143], v[0:15]
	s_waitcnt vmcnt(0)
	s_barrier
; #define MFMA32(a, b, c) __builtin_amdgcn_mfma_f32_32x32x16_bf16((a), (b), (c), 0, 0, 0)
; DI bfr f2bf(float a) { return (bfr)(pack2(a, 0.f) & 0xffffu); }
; template <int lda>
; DI void gemm_mainloop(const bfr* __restrict__ A, const bfr* __restrict__ Bt, int NB, int K, int m0, int n0, char* smem, f32x16 (&acc)[2][4]) {
;     ...
;     for (int ks = 0; ks < 2; ++ks) {
;       bf16x8 af[2], bfg[4];
; #pragma unroll
;       for (int i = 0; i < 2; ++i) af[i] = *(const bf16x8*)(As + (wr * 64 + i * 32 + r) * 40 + ks * 16 + hl * 8);
; #pragma unroll
;       for (int j = 0; j < 4; ++j) bfg[j] = *(const bf16x8*)(Bs + (wc * 128 + j * 32 + r) * 40 + ks * 16 + hl * 8);
; #pragma unroll
;       for (int i = 0; i < 2; ++i)
; #pragma unroll
;         for (int j = 0; j < 4; ++j) acc[i][j] = MFMA32(af[i], bfg[j], acc[i][j]);
; DI void phase_gemm_bf16out(const Params& p, const bfr* A, const bfr* Wt, bfr* C, int N, const float* ss, char* smem) {
;     ...
;     gemm_tile<1024>(A, Wt, N, 1024, mt * 128, nt * 256, smem,
;               [=](int row, int col, float v) {
;                 float inv = rsqrtf(ss[row] * (1.0f / 1024.0f) + EPSF);
;                 C[(size_t)row * N + col] = f2bf(v * inv);
;               });
	s_mul_i32 s74, s71, 0x6000
	s_add_u32 s75, s74, 0x2000
	s_cmp_eq_u32 s71, 2
	s_cselect_b32 s75, 0x10000, s75
	v_add_u32_e32 v183, s74, v179
	v_add_u32_e32 v185, s75, v181
	v_add_u32_e32 v184, s74, v180
	v_add_u32_e32 v186, s75, v182
	ds_read_b128 v[128:131], v183
	ds_read_b128 v[144:147], v185
	ds_read_b128 v[148:151], v185 offset:2048
	ds_read_b128 v[152:155], v185 offset:4096
	ds_read_b128 v[156:159], v185 offset:6144
	ds_read_b128 v[132:135], v183 offset:2048
	ds_read_b128 v[136:139], v184
	ds_read_b128 v[160:163], v186
	ds_read_b128 v[164:167], v186 offset:2048
	ds_read_b128 v[168:171], v186 offset:4096
	ds_read_b128 v[172:175], v186 offset:6144
	ds_read_b128 v[140:143], v184 offset:2048
	s_add_u32 s71, s71, 1
	s_cmp_eq_u32 s71, 3
	s_cselect_b32 s71, 0, s71
	s_waitcnt lgkmcnt(10)
	v_mfma_f32_32x32x16_bf16 v[112:127], v[144:147], v[128:131], v[112:127]
	s_waitcnt lgkmcnt(9)
	v_mfma_f32_32x32x16_bf16 v[96:111], v[148:151], v[128:131], v[96:111]
	s_waitcnt lgkmcnt(8)
	v_mfma_f32_32x32x16_bf16 v[80:95], v[152:155], v[128:131], v[80:95]
	s_waitcnt lgkmcnt(7)
	v_mfma_f32_32x32x16_bf16 v[64:79], v[156:159], v[128:131], v[64:79]
	s_waitcnt lgkmcnt(6)
	v_mfma_f32_32x32x16_bf16 v[48:63], v[144:147], v[132:135], v[48:63]
	v_mfma_f32_32x32x16_bf16 v[32:47], v[148:151], v[132:135], v[32:47]
	v_mfma_f32_32x32x16_bf16 v[16:31], v[152:155], v[132:135], v[16:31]
	v_mfma_f32_32x32x16_bf16 v[0:15], v[156:159], v[132:135], v[0:15]
	s_waitcnt lgkmcnt(4)
	v_mfma_f32_32x32x16_bf16 v[112:127], v[160:163], v[136:139], v[112:127]
	s_waitcnt lgkmcnt(3)
	v_mfma_f32_32x32x16_bf16 v[96:111], v[164:167], v[136:139], v[96:111]
	s_waitcnt lgkmcnt(2)
	v_mfma_f32_32x32x16_bf16 v[80:95], v[168:171], v[136:139], v[80:95]
	s_waitcnt lgkmcnt(1)
	v_mfma_f32_32x32x16_bf16 v[64:79], v[172:175], v[136:139], v[64:79]
	s_waitcnt lgkmcnt(0)
	v_mfma_f32_32x32x16_bf16 v[48:63], v[160:163], v[140:143], v[48:63]
	v_mfma_f32_32x32x16_bf16 v[32:47], v[164:167], v[140:143], v[32:47]
	v_mfma_f32_32x32x16_bf16 v[16:31], v[168:171], v[140:143], v[16:31]
	v_mfma_f32_32x32x16_bf16 v[0:15], v[172:175], v[140:143], v[0:15]
	s_nop 7
	s_nop 7
	s_load_dwordx2 s[64:65], s[92:93], 0x160
	s_load_dwordx2 s[66:67], s[92:93], 0x140
	v_and_b32_e32 v176, 31, v196
	v_bfe_u32 v177, v196, 5, 1
	s_lshr_b32 s74, s73, 1
	s_lshl_b32 s74, s74, 6
	s_add_u32 s74, s74, s77
	v_add_u32_e32 v178, s74, v176
	s_and_b32 s75, s73, 1
	s_lshl_b32 s75, s75, 7
	s_add_u32 s75, s75, s78
	v_lshl_add_u32 v179, v177, 2, s75
	v_mul_u32_u24_e32 v180, 0x400, v178
	v_add_lshl_u32 v181, v180, v179, 1
	v_add_u32_e32 v182, 0x10000, v181
	s_waitcnt lgkmcnt(0)
	v_lshlrev_b32_e32 v180, 2, v178
	global_load_dword v183, v180, s[66:67]
	global_load_dword v184, v180, s[66:67] offset:128
	s_waitcnt vmcnt(0)
	v_mul_f32_e32 v183, 0x3a800000, v183
	v_mul_f32_e32 v184, 0x3a800000, v184
	v_add_f32_e32 v183, 0x358637bd, v183
	v_add_f32_e32 v184, 0x358637bd, v184
	v_rsq_f32_e32 v183, v183
	v_rsq_f32_e32 v184, v184
	s_nop 1
	v_mul_f32_e32 v112, v183, v112
	v_mul_f32_e32 v113, v183, v113
	v_mul_f32_e32 v114, v183, v114
	v_mul_f32_e32 v115, v183, v115
	v_cvt_pk_bf16_f32 v112, v112, v113
	v_cvt_pk_bf16_f32 v113, v114, v115
	global_store_dwordx2 v181, v[112:113], s[64:65]
	v_mul_f32_e32 v116, v183, v116
	v_mul_f32_e32 v117, v183, v117
	v_mul_f32_e32 v118, v183, v118
	v_mul_f32_e32 v119, v183, v119
	v_cvt_pk_bf16_f32 v116, v116, v117
	v_cvt_pk_bf16_f32 v117, v118, v119
	global_store_dwordx2 v181, v[116:117], s[64:65] offset:16
	v_mul_f32_e32 v120, v183, v120
	v_mul_f32_e32 v121, v183, v121
	v_mul_f32_e32 v122, v183, v122
	v_mul_f32_e32 v123, v183, v123
	v_cvt_pk_bf16_f32 v120, v120, v121
	v_cvt_pk_bf16_f32 v121, v122, v123
	global_store_dwordx2 v181, v[120:121], s[64:65] offset:32
	v_mul_f32_e32 v124, v183, v124
	v_mul_f32_e32 v125, v183, v125
	v_mul_f32_e32 v126, v183, v126
	v_mul_f32_e32 v127, v183, v127
	v_cvt_pk_bf16_f32 v124, v124, v125
	v_cvt_pk_bf16_f32 v125, v126, v127
	global_store_dwordx2 v181, v[124:125], s[64:65] offset:48
	v_mul_f32_e32 v96, v183, v96
	v_mul_f32_e32 v97, v183, v97
	v_mul_f32_e32 v98, v183, v98
	v_mul_f32_e32 v99, v183, v99
	v_cvt_pk_bf16_f32 v96, v96, v97
	v_cvt_pk_bf16_f32 v97, v98, v99
	global_store_dwordx2 v181, v[96:97], s[64:65] offset:64
	v_mul_f32_e32 v100, v183, v100
	v_mul_f32_e32 v101, v183, v101
	v_mul_f32_e32 v102, v183, v102
	v_mul_f32_e32 v103, v183, v103
	v_cvt_pk_bf16_f32 v100, v100, v101
	v_cvt_pk_bf16_f32 v101, v102, v103
	global_store_dwordx2 v181, v[100:101], s[64:65] offset:80
	v_mul_f32_e32 v104, v183, v104
	v_mul_f32_e32 v105, v183, v105
	v_mul_f32_e32 v106, v183, v106
	v_mul_f32_e32 v107, v183, v107
	v_cvt_pk_bf16_f32 v104, v104, v105
	v_cvt_pk_bf16_f32 v105, v106, v107
	global_store_dwordx2 v181, v[104:105], s[64:65] offset:96
	v_mul_f32_e32 v108, v183, v108
	v_mul_f32_e32 v109, v183, v109
	v_mul_f32_e32 v110, v183, v110
	v_mul_f32_e32 v111, v183, v111
	v_cvt_pk_bf16_f32 v108, v108, v109
	v_cvt_pk_bf16_f32 v109, v110, v111
	global_store_dwordx2 v181, v[108:109], s[64:65] offset:112
	v_mul_f32_e32 v80, v183, v80
	v_mul_f32_e32 v81, v183, v81
	v_mul_f32_e32 v82, v183, v82
	v_mul_f32_e32 v83, v183, v83
	v_cvt_pk_bf16_f32 v80, v80, v81
	v_cvt_pk_bf16_f32 v81, v82, v83
	global_store_dwordx2 v181, v[80:81], s[64:65] offset:128
	v_mul_f32_e32 v84, v183, v84
	v_mul_f32_e32 v85, v183, v85
	v_mul_f32_e32 v86, v183, v86
	v_mul_f32_e32 v87, v183, v87
	v_cvt_pk_bf16_f32 v84, v84, v85
	v_cvt_pk_bf16_f32 v85, v86, v87
	global_store_dwordx2 v181, v[84:85], s[64:65] offset:144
	v_mul_f32_e32 v88, v183, v88
	v_mul_f32_e32 v89, v183, v89
	v_mul_f32_e32 v90, v183, v90
	v_mul_f32_e32 v91, v183, v91
	v_cvt_pk_bf16_f32 v88, v88, v89
; DI bfr f2bf(float a) { return (bfr)(pack2(a, 0.f) & 0xffffu); }
; DI void phase_gemm_bf16out(const Params& p, const bfr* A, const bfr* Wt, bfr* C, int N, const float* ss, char* smem) {
;     ...
;   for (int t0 = blockIdx.x; t0 < 128 * ntn; t0 += gridDim.x) {
;     const int t = ((gridDim.x & 7) == 0) ? xcd_tile(t0, ntn) : t0;
;     int mt = t / ntn, nt = t % ntn;
;     gemm_tile<1024>(A, Wt, N, 1024, mt * 128, nt * 256, smem,
;               [=](int row, int col, float v) {
;                 float inv = rsqrtf(ss[row] * (1.0f / 1024.0f) + EPSF);
;                 C[(size_t)row * N + col] = f2bf(v * inv);
;               });
	v_cvt_pk_bf16_f32 v89, v90, v91
	global_store_dwordx2 v181, v[88:89], s[64:65] offset:160
	v_mul_f32_e32 v92, v183, v92
	v_mul_f32_e32 v93, v183, v93
	v_mul_f32_e32 v94, v183, v94
	v_mul_f32_e32 v95, v183, v95
	v_cvt_pk_bf16_f32 v92, v92, v93
	v_cvt_pk_bf16_f32 v93, v94, v95
	global_store_dwordx2 v181, v[92:93], s[64:65] offset:176
	v_mul_f32_e32 v64, v183, v64
	v_mul_f32_e32 v65, v183, v65
	v_mul_f32_e32 v66, v183, v66
	v_mul_f32_e32 v67, v183, v67
	v_cvt_pk_bf16_f32 v64, v64, v65
	v_cvt_pk_bf16_f32 v65, v66, v67
	global_store_dwordx2 v181, v[64:65], s[64:65] offset:192
	v_mul_f32_e32 v68, v183, v68
	v_mul_f32_e32 v69, v183, v69
	v_mul_f32_e32 v70, v183, v70
	v_mul_f32_e32 v71, v183, v71
	v_cvt_pk_bf16_f32 v68, v68, v69
	v_cvt_pk_bf16_f32 v69, v70, v71
	global_store_dwordx2 v181, v[68:69], s[64:65] offset:208
	v_mul_f32_e32 v72, v183, v72
	v_mul_f32_e32 v73, v183, v73
	v_mul_f32_e32 v74, v183, v74
	v_mul_f32_e32 v75, v183, v75
	v_cvt_pk_bf16_f32 v72, v72, v73
	v_cvt_pk_bf16_f32 v73, v74, v75
	global_store_dwordx2 v181, v[72:73], s[64:65] offset:224
	v_mul_f32_e32 v76, v183, v76
	v_mul_f32_e32 v77, v183, v77
	v_mul_f32_e32 v78, v183, v78
	v_mul_f32_e32 v79, v183, v79
	v_cvt_pk_bf16_f32 v76, v76, v77
	v_cvt_pk_bf16_f32 v77, v78, v79
	global_store_dwordx2 v181, v[76:77], s[64:65] offset:240
	v_mul_f32_e32 v48, v184, v48
	v_mul_f32_e32 v49, v184, v49
	v_mul_f32_e32 v50, v184, v50
	v_mul_f32_e32 v51, v184, v51
	v_cvt_pk_bf16_f32 v48, v48, v49
	v_cvt_pk_bf16_f32 v49, v50, v51
	global_store_dwordx2 v182, v[48:49], s[64:65]
	v_mul_f32_e32 v52, v184, v52
	v_mul_f32_e32 v53, v184, v53
	v_mul_f32_e32 v54, v184, v54
	v_mul_f32_e32 v55, v184, v55
	v_cvt_pk_bf16_f32 v52, v52, v53
	v_cvt_pk_bf16_f32 v53, v54, v55
	global_store_dwordx2 v182, v[52:53], s[64:65] offset:16
	v_mul_f32_e32 v56, v184, v56
	v_mul_f32_e32 v57, v184, v57
	v_mul_f32_e32 v58, v184, v58
	v_mul_f32_e32 v59, v184, v59
	v_cvt_pk_bf16_f32 v56, v56, v57
	v_cvt_pk_bf16_f32 v57, v58, v59
	global_store_dwordx2 v182, v[56:57], s[64:65] offset:32
	v_mul_f32_e32 v60, v184, v60
	v_mul_f32_e32 v61, v184, v61
	v_mul_f32_e32 v62, v184, v62
	v_mul_f32_e32 v63, v184, v63
	v_cvt_pk_bf16_f32 v60, v60, v61
	v_cvt_pk_bf16_f32 v61, v62, v63
	global_store_dwordx2 v182, v[60:61], s[64:65] offset:48
	v_mul_f32_e32 v32, v184, v32
	v_mul_f32_e32 v33, v184, v33
	v_mul_f32_e32 v34, v184, v34
	v_mul_f32_e32 v35, v184, v35
	v_cvt_pk_bf16_f32 v32, v32, v33
	v_cvt_pk_bf16_f32 v33, v34, v35
	global_store_dwordx2 v182, v[32:33], s[64:65] offset:64
	v_mul_f32_e32 v36, v184, v36
	v_mul_f32_e32 v37, v184, v37
	v_mul_f32_e32 v38, v184, v38
	v_mul_f32_e32 v39, v184, v39
	v_cvt_pk_bf16_f32 v36, v36, v37
	v_cvt_pk_bf16_f32 v37, v38, v39
	global_store_dwordx2 v182, v[36:37], s[64:65] offset:80
	v_mul_f32_e32 v40, v184, v40
	v_mul_f32_e32 v41, v184, v41
	v_mul_f32_e32 v42, v184, v42
	v_mul_f32_e32 v43, v184, v43
	v_cvt_pk_bf16_f32 v40, v40, v41
	v_cvt_pk_bf16_f32 v41, v42, v43
	global_store_dwordx2 v182, v[40:41], s[64:65] offset:96
	v_mul_f32_e32 v44, v184, v44
	v_mul_f32_e32 v45, v184, v45
	v_mul_f32_e32 v46, v184, v46
	v_mul_f32_e32 v47, v184, v47
	v_cvt_pk_bf16_f32 v44, v44, v45
	v_cvt_pk_bf16_f32 v45, v46, v47
	global_store_dwordx2 v182, v[44:45], s[64:65] offset:112
	v_mul_f32_e32 v16, v184, v16
	v_mul_f32_e32 v17, v184, v17
	v_mul_f32_e32 v18, v184, v18
	v_mul_f32_e32 v19, v184, v19
	v_cvt_pk_bf16_f32 v16, v16, v17
	v_cvt_pk_bf16_f32 v17, v18, v19
	global_store_dwordx2 v182, v[16:17], s[64:65] offset:128
	v_mul_f32_e32 v20, v184, v20
	v_mul_f32_e32 v21, v184, v21
	v_mul_f32_e32 v22, v184, v22
	v_mul_f32_e32 v23, v184, v23
	v_cvt_pk_bf16_f32 v20, v20, v21
	v_cvt_pk_bf16_f32 v21, v22, v23
	global_store_dwordx2 v182, v[20:21], s[64:65] offset:144
	v_mul_f32_e32 v24, v184, v24
	v_mul_f32_e32 v25, v184, v25
	v_mul_f32_e32 v26, v184, v26
	v_mul_f32_e32 v27, v184, v27
	v_cvt_pk_bf16_f32 v24, v24, v25
	v_cvt_pk_bf16_f32 v25, v26, v27
	global_store_dwordx2 v182, v[24:25], s[64:65] offset:160
	v_mul_f32_e32 v28, v184, v28
	v_mul_f32_e32 v29, v184, v29
	v_mul_f32_e32 v30, v184, v30
	v_mul_f32_e32 v31, v184, v31
	v_cvt_pk_bf16_f32 v28, v28, v29
	v_cvt_pk_bf16_f32 v29, v30, v31
	global_store_dwordx2 v182, v[28:29], s[64:65] offset:176
	v_mul_f32_e32 v0, v184, v0
	v_mul_f32_e32 v1, v184, v1
	v_mul_f32_e32 v2, v184, v2
	v_mul_f32_e32 v3, v184, v3
	v_cvt_pk_bf16_f32 v0, v0, v1
	v_cvt_pk_bf16_f32 v1, v2, v3
	global_store_dwordx2 v182, v[0:1], s[64:65] offset:192
	v_mul_f32_e32 v4, v184, v4
	v_mul_f32_e32 v5, v184, v5
	v_mul_f32_e32 v6, v184, v6
	v_mul_f32_e32 v7, v184, v7
	v_cvt_pk_bf16_f32 v4, v4, v5
	v_cvt_pk_bf16_f32 v5, v6, v7
	global_store_dwordx2 v182, v[4:5], s[64:65] offset:208
	v_mul_f32_e32 v8, v184, v8
	v_mul_f32_e32 v9, v184, v9
	v_mul_f32_e32 v10, v184, v10
	v_mul_f32_e32 v11, v184, v11
	v_cvt_pk_bf16_f32 v8, v8, v9
	v_cvt_pk_bf16_f32 v9, v10, v11
	global_store_dwordx2 v182, v[8:9], s[64:65] offset:224
	v_mul_f32_e32 v12, v184, v12
	v_mul_f32_e32 v13, v184, v13
	v_mul_f32_e32 v14, v184, v14
	v_mul_f32_e32 v15, v184, v15
	v_cvt_pk_bf16_f32 v12, v12, v13
	v_cvt_pk_bf16_f32 v13, v14, v15
	global_store_dwordx2 v182, v[12:13], s[64:65] offset:240
	v_readlane_b32 s64, v187, 0
	v_readlane_b32 s65, v187, 1
	v_readlane_b32 s66, v187, 2
	v_readlane_b32 s67, v187, 3
	v_readlane_b32 s68, v187, 4
	v_readlane_b32 s69, v187, 5
	v_readlane_b32 s70, v187, 6
	v_readlane_b32 s71, v187, 7
	v_readlane_b32 s72, v187, 8
	v_readlane_b32 s73, v187, 9
	v_readlane_b32 s74, v187, 10
	v_readlane_b32 s75, v187, 11
	v_readlane_b32 s76, v187, 12
	v_readlane_b32 s77, v187, 13
	v_readlane_b32 s78, v187, 14
	v_readlane_b32 s79, v187, 15
	s_nop 7
	s_add_i32 s28, s28, s34
	s_cmpk_lt_i32 s28, 0x200
	s_cbranch_scc0 .LBB0_936
	s_branch .LBB0_923
